# mLSTM q/k projection GEMM: K loop restricted to the block-diagonal weight's nonzero K range per column tile (4 of 8 K-steps)
# speedup vs baseline: 1.0125x; 1.0074x over previous
.LBB0_886:
	v_readlane_b32 s0, v254, 5
	v_readlane_b32 s1, v254, 0
	v_mov_b32_e32 v2, v163
	s_waitcnt vmcnt(0) lgkmcnt(0)
	s_barrier
	s_cmpk_gt_i32 s1, 0x17f
	v_readfirstlane_b32 s2, v2
	s_cbranch_scc1 .LBB0_898
	v_lshlrev_b32_e32 v0, 4, v2
	v_add_u32_e32 v4, 0x2000, v0
	v_ashrrev_i32_e32 v3, 31, v4
	v_lshrrev_b32_e32 v3, 22, v3
	v_add_u32_e32 v3, v4, v3
	v_ashrrev_i32_e32 v3, 10, v3
	v_readlane_b32 s4, v254, 25
	v_lshlrev_b32_e32 v5, 5, v3
	v_readlane_b32 s5, v254, 26
	v_and_b32_e32 v6, 32, v5
	v_mul_i32_i24_e32 v5, 0x400, v3
	s_load_dwordx2 s[4:5], s[4:5], 0x118
	v_sub_u32_e32 v4, v4, v5
	v_lshrrev_b32_e32 v5, 4, v4
	v_bitop3_b32 v5, v5, v4, 32 bitop3:0x6c
	v_ashrrev_i32_e32 v4, 31, v5
	v_lshrrev_b32_e32 v4, 26, v4
	s_waitcnt lgkmcnt(0)
	s_add_u32 s3, s4, 0x34b4000
	v_add_u32_e32 v7, v5, v4
	s_addc_u32 s24, s5, 0
	v_ashrrev_i32_e32 v4, 6, v7
	v_and_b32_e32 v7, 0xc0, v7
	s_add_u32 s25, s4, 0x634000
	v_sub_u32_e32 v5, v5, v7
	s_addc_u32 s26, s5, 0
	v_ashrrev_i16_sdwa v5, v171, sext(v5) dst_sel:DWORD dst_unused:UNUSED_PAD src0_sel:DWORD src1_sel:BYTE_0
	v_lshlrev_b32_e32 v7, 3, v3
	s_ashr_i32 s28, s1, 31
	v_bfe_i32 v5, v5, 0, 16
	v_and_b32_e32 v7, 0x3ffff0, v7
	s_lshr_b32 s4, s28, 29
	v_add_u32_e32 v6, v6, v5
	v_add_lshl_u32 v7, v4, v7, 10
	s_add_i32 s4, s1, s4
	s_ashr_i32 s5, s2, 6
	v_lshl_add_u32 v130, v6, 1, v7
	v_ashrrev_i32_e32 v6, 31, v2
	s_ashr_i32 s6, s4, 3
	s_and_b32 s4, s4, -8
	s_ashr_i32 s10, s2, 8
	s_lshl_b32 s27, s5, 10
	v_lshrrev_b32_e32 v6, 26, v6
	s_sub_i32 s4, s1, s4
	v_add_u32_e32 v6, v2, v6
	s_cmp_lt_i32 s4, 0
	v_ashrrev_i32_e32 v6, 6, v6
	s_cselect_b32 s7, 49, 48
	v_lshlrev_b32_e32 v7, 5, v6
	s_mul_i32 s4, s7, s4
	v_and_b32_e32 v9, 32, v7
	v_bfe_i32 v7, v2, 27, 1
	s_add_i32 s4, s4, s6
	v_lshrrev_b32_e32 v7, 22, v7
	s_ashr_i32 s6, s4, 31
	v_add_u32_e32 v7, v0, v7
	s_lshr_b32 s6, s6, 28
	v_and_b32_e32 v7, 0xfffffc00, v7
	s_add_i32 s6, s4, s6
	v_sub_u32_e32 v0, v0, v7
	s_ashr_i32 s7, s6, 4
	s_and_b32 s6, s6, 0xfff0
	v_lshrrev_b32_e32 v7, 4, v0
	s_sub_i32 s6, s4, s6
	v_bitop3_b32 v8, v7, v0, 32 bitop3:0x6c
	v_ashrrev_i32_e32 v0, 31, v0
	s_bfe_i32 s4, s6, 0x80000
	v_lshrrev_b32_e32 v0, 26, v0
	s_bfe_u32 s4, s4, 0x2000d
	v_add_u32_e32 v0, v8, v0
	s_add_i32 s8, s6, s4
	v_ashrrev_i32_e32 v7, 6, v0
	s_bfe_i32 s4, s8, 0x80000
	s_and_b32 s8, s8, 0xfc
	v_mul_i32_i24_e32 v0, 64, v7
	s_sub_i32 s6, s6, s8
	v_sub_u32_e32 v0, v8, v0
	s_lshl_b32 s7, s7, 2
	s_sext_i32_i16 s4, s4
	s_sext_i32_i8 s6, s6
	v_ashrrev_i16_sdwa v0, v171, sext(v0) dst_sel:DWORD dst_unused:UNUSED_PAD src0_sel:DWORD src1_sel:BYTE_0
	s_lshr_b32 s4, s4, 2
	s_add_i32 s6, s7, s6
	v_bfe_i32 v8, v0, 0, 16
	s_ashr_i32 s7, s6, 31
	s_bfe_i64 s[8:9], s[4:5], 0x100000
	v_add_u32_e32 v0, v9, v8
	v_lshlrev_b32_e32 v9, 3, v6
	s_lshl_b64 s[12:13], s[6:7], 18
	s_lshl_b64 s[8:9], s[8:9], 18
	v_and_b32_e32 v9, 0x3ffff0, v9
	s_add_u32 s8, s25, s8
	v_add_lshl_u32 v9, v7, v9, 10
	s_addc_u32 s9, s26, s9
	s_and_b32 s98, s4, 1
	s_lshl_b32 s98, s98, 9
	s_add_u32 s8, s8, s98
	s_addc_u32 s9, s9, 0
	s_add_i32 s29, s27, 0
	v_lshl_add_u32 v0, v0, 1, v9
	s_add_i32 m0, s29, 0x10000
	s_nop 0
	global_load_lds_dwordx4 v0, s[8:9]
	s_add_i32 m0, s29, 0x12000
	s_add_u32 s20, s3, s12
	global_load_lds_dwordx4 v130, s[8:9]
	s_addc_u32 s21, s24, s13
	s_add_u32 s20, s20, s98
	s_addc_u32 s21, s21, 0
	s_mov_b32 m0, s29
	s_add_i32 s30, s29, 0x2000
	global_load_lds_dwordx4 v0, s[20:21]
	s_mov_b32 m0, s30
	s_add_u32 s12, s8, 0x20000
	global_load_lds_dwordx4 v130, s[20:21]
	s_addc_u32 s13, s9, 0
	s_add_i32 m0, s29, 0x14000
	s_nop 0
	global_load_lds_dwordx4 v0, s[12:13]
	s_add_i32 m0, s29, 0x16000
	s_nop 0
	global_load_lds_dwordx4 v130, s[12:13]
	s_add_u32 s12, s20, 0x20000
	s_addc_u32 s13, s21, 0
	s_add_i32 s31, s29, 0x4000
	s_mov_b32 m0, s31
	s_add_i32 s34, s29, 0x6000
	global_load_lds_dwordx4 v0, s[12:13]
	s_mov_b32 m0, s34
	s_cmp_lg_u32 s10, 1
	global_load_lds_dwordx4 v130, s[12:13]
	s_cbranch_scc1 .LBB0_889
	s_barrier

.LBB0_892:
	s_ashr_i32 s13, s12, 31
	v_cmp_lt_i64_e32 vcc, s[16:17], v[166:167]
	s_lshl_b64 s[16:17], s[12:13], 18
	s_add_u32 s16, s3, s16
	s_addc_u32 s17, s24, s17
	s_and_b32 s98, s10, 1
	s_lshl_b32 s98, s98, 9
	s_add_u32 s16, s16, s98
	s_addc_u32 s17, s17, 0
	s_and_b64 s[18:19], vcc, exec
	s_cselect_b32 s13, s17, s21
	s_cselect_b32 s39, s16, s20
	s_ashr_i32 s11, s10, 31
	s_lshl_b64 s[18:19], s[10:11], 18
	s_add_u32 s18, s25, s18
	s_addc_u32 s19, s26, s19
	s_add_u32 s18, s18, s98
	s_addc_u32 s19, s19, 0
	s_and_b64 s[22:23], vcc, exec
	s_cselect_b32 s11, s19, s9
	s_cselect_b32 s40, s18, s8
	s_add_u32 s41, s8, 0x100
	s_addc_u32 s42, s9, 0
	s_add_u32 s8, s20, 0x20080
	v_mov_b32_e32 v2, 0
	s_addc_u32 s9, s21, 0
	s_mov_b32 s43, -2
	v_mov_b32_e32 v3, v2
	v_mov_b32_e32 v4, v2
	v_mov_b32_e32 v5, v2
	v_mov_b32_e32 v6, v2
	v_mov_b32_e32 v7, v2
	v_mov_b32_e32 v8, v2
	v_mov_b32_e32 v9, v2
	v_mov_b32_e32 v14, v2
	v_mov_b32_e32 v15, v2
	v_mov_b32_e32 v16, v2
	v_mov_b32_e32 v17, v2
	v_mov_b32_e32 v22, v2
	v_mov_b32_e32 v23, v2
	v_mov_b32_e32 v24, v2
	v_mov_b32_e32 v25, v2
	v_mov_b32_e32 v30, v2
	v_mov_b32_e32 v31, v2
	v_mov_b32_e32 v32, v2
	v_mov_b32_e32 v33, v2
	v_mov_b32_e32 v38, v2
	v_mov_b32_e32 v39, v2
	v_mov_b32_e32 v40, v2
	v_mov_b32_e32 v41, v2
	v_mov_b32_e32 v46, v2
	v_mov_b32_e32 v47, v2
	v_mov_b32_e32 v48, v2
	v_mov_b32_e32 v49, v2
	v_mov_b32_e32 v54, v2
	v_mov_b32_e32 v55, v2
	v_mov_b32_e32 v56, v2
	v_mov_b32_e32 v57, v2
	v_mov_b32_e32 v10, v2
	v_mov_b32_e32 v11, v2
	v_mov_b32_e32 v12, v2
	v_mov_b32_e32 v13, v2
	v_mov_b32_e32 v18, v2
	v_mov_b32_e32 v19, v2
	v_mov_b32_e32 v20, v2
	v_mov_b32_e32 v21, v2
	v_mov_b32_e32 v26, v2
	v_mov_b32_e32 v27, v2
	v_mov_b32_e32 v28, v2
	v_mov_b32_e32 v29, v2
	v_mov_b32_e32 v34, v2
	v_mov_b32_e32 v35, v2
	v_mov_b32_e32 v36, v2
	v_mov_b32_e32 v37, v2
	v_mov_b32_e32 v42, v2
	v_mov_b32_e32 v43, v2
	v_mov_b32_e32 v44, v2
	v_mov_b32_e32 v45, v2
	v_mov_b32_e32 v50, v2
	v_mov_b32_e32 v51, v2
	v_mov_b32_e32 v52, v2
	v_mov_b32_e32 v53, v2
	v_mov_b32_e32 v58, v2
	v_mov_b32_e32 v59, v2
	v_mov_b32_e32 v60, v2
	v_mov_b32_e32 v61, v2
	v_mov_b32_e32 v62, v2
	v_mov_b32_e32 v63, v2
	v_mov_b32_e32 v64, v2
	v_mov_b32_e32 v65, v2
	v_mov_b32_e32 v66, v2
	v_mov_b32_e32 v67, v2
	v_mov_b32_e32 v68, v2
	v_mov_b32_e32 v69, v2
	v_mov_b32_e32 v70, v2
	v_mov_b32_e32 v71, v2
	v_mov_b32_e32 v72, v2
	v_mov_b32_e32 v73, v2
	v_mov_b32_e32 v78, v2
	v_mov_b32_e32 v79, v2
	v_mov_b32_e32 v80, v2
	v_mov_b32_e32 v81, v2
	v_mov_b32_e32 v86, v2
	v_mov_b32_e32 v87, v2
	v_mov_b32_e32 v88, v2
	v_mov_b32_e32 v89, v2
	v_mov_b32_e32 v94, v2
	v_mov_b32_e32 v95, v2
	v_mov_b32_e32 v96, v2
	v_mov_b32_e32 v97, v2
	v_mov_b32_e32 v102, v2
	v_mov_b32_e32 v103, v2
	v_mov_b32_e32 v104, v2
	v_mov_b32_e32 v105, v2
	v_mov_b32_e32 v110, v2
	v_mov_b32_e32 v111, v2
	v_mov_b32_e32 v112, v2
	v_mov_b32_e32 v113, v2
	v_mov_b32_e32 v118, v2
	v_mov_b32_e32 v119, v2
	v_mov_b32_e32 v120, v2
	v_mov_b32_e32 v121, v2
	v_mov_b32_e32 v74, v2
	v_mov_b32_e32 v75, v2
	v_mov_b32_e32 v76, v2
	v_mov_b32_e32 v77, v2
	v_mov_b32_e32 v82, v2
	v_mov_b32_e32 v83, v2
	v_mov_b32_e32 v84, v2
	v_mov_b32_e32 v85, v2
	v_mov_b32_e32 v90, v2
	v_mov_b32_e32 v91, v2
	v_mov_b32_e32 v92, v2
	v_mov_b32_e32 v93, v2
	v_mov_b32_e32 v98, v2
	v_mov_b32_e32 v99, v2
	v_mov_b32_e32 v100, v2
	v_mov_b32_e32 v101, v2
	v_mov_b32_e32 v106, v2
	v_mov_b32_e32 v107, v2
	v_mov_b32_e32 v108, v2
	v_mov_b32_e32 v109, v2
	v_mov_b32_e32 v114, v2
	v_mov_b32_e32 v115, v2
	v_mov_b32_e32 v116, v2
	v_mov_b32_e32 v117, v2
	v_mov_b32_e32 v122, v2
	v_mov_b32_e32 v123, v2
	v_mov_b32_e32 v124, v2
	v_mov_b32_e32 v125, v2
	v_mov_b32_e32 v126, v2
	v_mov_b32_e32 v127, v2
	v_mov_b32_e32 v128, v2
	v_mov_b32_e32 v129, v2
.LBB0_893:
	s_add_u32 s20, s8, 0xfffe0080
	s_addc_u32 s21, s9, -1
	s_add_i32 s44, 0, 0x10000
	v_add_u32_e32 v150, s44, v136
	ds_read_b128 v[138:141], v150
	ds_read_b128 v[142:145], v150 offset:1024
	ds_read_b128 v[146:149], v150 offset:2048
	ds_read_b128 v[150:153], v150 offset:3072
	s_cmp_eq_u32 s43, 0
	s_cselect_b32 s23, s13, s21
	s_cselect_b32 s22, s39, s20
	s_cselect_b32 s21, s11, s42
	s_cselect_b32 s20, s40, s41
	v_lshl_add_u64 v[200:201], s[8:9], 0, v[134:135]
	s_add_i32 m0, s29, 0xc000
	ds_read_b128 v[154:157], v137
	ds_read_b128 v[158:161], v137 offset:1024
	ds_read_b128 v[176:179], v137 offset:2048
	ds_read_b128 v[180:183], v137 offset:3072
	ds_read_b128 v[184:187], v137 offset:4096
	ds_read_b128 v[188:191], v137 offset:5120
	ds_read_b128 v[192:195], v137 offset:6144
	ds_read_b128 v[196:199], v137 offset:7168
	global_load_lds_dwordx4 v[200:201], off
	v_lshl_add_u64 v[200:201], s[8:9], 0, v[132:133]
	s_add_i32 m0, s29, 0xe000
	s_nop 0
	global_load_lds_dwordx4 v[200:201], off
	s_waitcnt lgkmcnt(8)
	s_barrier
	s_waitcnt lgkmcnt(0)
	s_setprio 1
	s_waitcnt lgkmcnt(0)
	v_mfma_f32_16x16x32_bf16 v[126:129], v[138:141], v[154:157], v[126:129]
	v_mfma_f32_16x16x32_bf16 v[122:125], v[146:149], v[154:157], v[122:125]
	v_mfma_f32_16x16x32_bf16 v[114:117], v[138:141], v[176:179], v[114:117]
	v_mfma_f32_16x16x32_bf16 v[106:109], v[146:149], v[176:179], v[106:109]
	v_mfma_f32_16x16x32_bf16 v[98:101], v[138:141], v[184:187], v[98:101]
	v_mfma_f32_16x16x32_bf16 v[90:93], v[146:149], v[184:187], v[90:93]
	v_mfma_f32_16x16x32_bf16 v[82:85], v[138:141], v[192:195], v[82:85]
	v_mfma_f32_16x16x32_bf16 v[74:77], v[146:149], v[192:195], v[74:77]
	v_mfma_f32_16x16x32_bf16 v[126:129], v[142:145], v[158:161], v[126:129]
	v_mfma_f32_16x16x32_bf16 v[122:125], v[150:153], v[158:161], v[122:125]
	v_mfma_f32_16x16x32_bf16 v[114:117], v[142:145], v[180:183], v[114:117]
	v_mfma_f32_16x16x32_bf16 v[106:109], v[150:153], v[180:183], v[106:109]
	v_mfma_f32_16x16x32_bf16 v[98:101], v[142:145], v[188:191], v[98:101]
	v_mfma_f32_16x16x32_bf16 v[90:93], v[150:153], v[188:191], v[90:93]
	v_mfma_f32_16x16x32_bf16 v[82:85], v[142:145], v[196:199], v[82:85]
	v_mfma_f32_16x16x32_bf16 v[74:77], v[150:153], v[196:199], v[74:77]
	s_setprio 0
	s_barrier
	s_add_i32 s46, 0, 0x14000
	s_add_i32 s44, s44, s27
	v_add_u32_e32 v169, s46, v136
	v_lshl_add_u64 v[200:201], s[20:21], 0, v[0:1]
	s_mov_b32 m0, s44
	ds_read_b128 v[230:233], v169
	ds_read_b128 v[234:237], v169 offset:1024
	ds_read_b128 v[238:241], v169 offset:2048
	ds_read_b128 v[242:245], v169 offset:3072
	global_load_lds_dwordx4 v[200:201], off
	v_lshl_add_u64 v[246:247], s[20:21], 0, v[130:131]
	s_add_i32 m0, s44, 0x2000
	s_nop 0
	global_load_lds_dwordx4 v[246:247], off
	s_barrier
	s_waitcnt lgkmcnt(0)
	s_setprio 1
	s_waitcnt lgkmcnt(0)
	v_mfma_f32_16x16x32_bf16 v[118:121], v[230:233], v[154:157], v[118:121]
	v_mfma_f32_16x16x32_bf16 v[110:113], v[238:241], v[154:157], v[110:113]
	v_mfma_f32_16x16x32_bf16 v[102:105], v[230:233], v[176:179], v[102:105]
	v_mfma_f32_16x16x32_bf16 v[94:97], v[238:241], v[176:179], v[94:97]
	v_mfma_f32_16x16x32_bf16 v[86:89], v[230:233], v[184:187], v[86:89]
	v_mfma_f32_16x16x32_bf16 v[78:81], v[238:241], v[184:187], v[78:81]
	v_mfma_f32_16x16x32_bf16 v[70:73], v[230:233], v[192:195], v[70:73]
	v_mfma_f32_16x16x32_bf16 v[66:69], v[238:241], v[192:195], v[66:69]
	v_mfma_f32_16x16x32_bf16 v[118:121], v[234:237], v[158:161], v[118:121]
	v_mfma_f32_16x16x32_bf16 v[110:113], v[242:245], v[158:161], v[110:113]
	v_mfma_f32_16x16x32_bf16 v[102:105], v[234:237], v[180:183], v[102:105]
	v_mfma_f32_16x16x32_bf16 v[94:97], v[242:245], v[180:183], v[94:97]
	v_mfma_f32_16x16x32_bf16 v[86:89], v[234:237], v[188:191], v[86:89]
	v_mfma_f32_16x16x32_bf16 v[78:81], v[242:245], v[188:191], v[78:81]
	v_mfma_f32_16x16x32_bf16 v[70:73], v[234:237], v[196:199], v[70:73]
	v_mfma_f32_16x16x32_bf16 v[66:69], v[242:245], v[196:199], v[66:69]
	s_setprio 0
	s_mov_b32 m0, s29
	v_lshl_add_u64 v[248:249], s[22:23], 0, v[0:1]
	s_barrier
	ds_read_b128 v[154:157], v137 offset:16384
	ds_read_b128 v[158:161], v137 offset:17408
	ds_read_b128 v[176:179], v137 offset:18432
	ds_read_b128 v[180:183], v137 offset:19456
	ds_read_b128 v[184:187], v137 offset:20480
	ds_read_b128 v[188:191], v137 offset:21504
	ds_read_b128 v[192:195], v137 offset:22528
	ds_read_b128 v[196:199], v137 offset:23552
	global_load_lds_dwordx4 v[248:249], off
	v_lshl_add_u64 v[250:251], s[22:23], 0, v[130:131]
	s_mov_b32 m0, s30
	s_nop 0
	global_load_lds_dwordx4 v[250:251], off
	s_barrier
	s_waitcnt lgkmcnt(0)
	s_setprio 1
	s_waitcnt lgkmcnt(0)
	v_mfma_f32_16x16x32_bf16 v[62:65], v[138:141], v[154:157], v[62:65]
	v_mfma_f32_16x16x32_bf16 v[58:61], v[146:149], v[154:157], v[58:61]
	v_mfma_f32_16x16x32_bf16 v[50:53], v[138:141], v[176:179], v[50:53]
	v_mfma_f32_16x16x32_bf16 v[42:45], v[146:149], v[176:179], v[42:45]
	v_mfma_f32_16x16x32_bf16 v[34:37], v[138:141], v[184:187], v[34:37]
	v_mfma_f32_16x16x32_bf16 v[26:29], v[146:149], v[184:187], v[26:29]
	v_mfma_f32_16x16x32_bf16 v[18:21], v[138:141], v[192:195], v[18:21]
	v_mfma_f32_16x16x32_bf16 v[10:13], v[146:149], v[192:195], v[10:13]
	v_mfma_f32_16x16x32_bf16 v[62:65], v[142:145], v[158:161], v[62:65]
	v_mfma_f32_16x16x32_bf16 v[58:61], v[150:153], v[158:161], v[58:61]
	v_mfma_f32_16x16x32_bf16 v[50:53], v[142:145], v[180:183], v[50:53]
	v_mfma_f32_16x16x32_bf16 v[42:45], v[150:153], v[180:183], v[42:45]
	v_mfma_f32_16x16x32_bf16 v[34:37], v[142:145], v[188:191], v[34:37]
	v_mfma_f32_16x16x32_bf16 v[26:29], v[150:153], v[188:191], v[26:29]
	v_mfma_f32_16x16x32_bf16 v[18:21], v[142:145], v[196:199], v[18:21]
	v_mfma_f32_16x16x32_bf16 v[10:13], v[150:153], v[196:199], v[10:13]
	s_setprio 0
	s_barrier
	s_add_u32 s44, s20, 0x20000
	s_addc_u32 s45, s21, 0
	s_add_i32 s46, s46, s27
	v_lshl_add_u64 v[138:139], s[44:45], 0, v[0:1]
	s_mov_b32 m0, s46
	s_nop 0
	global_load_lds_dwordx4 v[138:139], off
	v_lshl_add_u64 v[138:139], s[44:45], 0, v[130:131]
	s_add_i32 m0, s46, 0x2000
	s_nop 0
	global_load_lds_dwordx4 v[138:139], off
	s_waitcnt vmcnt(6)
	s_barrier
	s_setprio 1
	v_mfma_f32_16x16x32_bf16 v[54:57], v[230:233], v[154:157], v[54:57]
	v_mfma_f32_16x16x32_bf16 v[46:49], v[238:241], v[154:157], v[46:49]
	v_mfma_f32_16x16x32_bf16 v[38:41], v[230:233], v[176:179], v[38:41]
	v_mfma_f32_16x16x32_bf16 v[30:33], v[238:241], v[176:179], v[30:33]
	v_mfma_f32_16x16x32_bf16 v[22:25], v[230:233], v[184:187], v[22:25]
	v_mfma_f32_16x16x32_bf16 v[14:17], v[238:241], v[184:187], v[14:17]
	v_mfma_f32_16x16x32_bf16 v[6:9], v[230:233], v[192:195], v[6:9]
	v_mfma_f32_16x16x32_bf16 v[2:5], v[238:241], v[192:195], v[2:5]
	v_mfma_f32_16x16x32_bf16 v[54:57], v[234:237], v[158:161], v[54:57]
	v_mfma_f32_16x16x32_bf16 v[46:49], v[242:245], v[158:161], v[46:49]
	v_mfma_f32_16x16x32_bf16 v[38:41], v[234:237], v[180:183], v[38:41]
	v_mfma_f32_16x16x32_bf16 v[30:33], v[242:245], v[180:183], v[30:33]
	v_mfma_f32_16x16x32_bf16 v[22:25], v[234:237], v[188:191], v[22:25]
	v_mfma_f32_16x16x32_bf16 v[14:17], v[242:245], v[188:191], v[14:17]
	v_mfma_f32_16x16x32_bf16 v[6:9], v[234:237], v[196:199], v[6:9]
	v_mfma_f32_16x16x32_bf16 v[2:5], v[242:245], v[196:199], v[2:5]
	s_setprio 0
	s_add_i32 s44, 0, 0x18000
	v_add_u32_e32 v150, s44, v136
	s_barrier
	ds_read_b128 v[138:141], v150
	ds_read_b128 v[142:145], v150 offset:1024
	ds_read_b128 v[146:149], v150 offset:2048
	ds_read_b128 v[150:153], v150 offset:3072
	s_add_u32 s22, s22, 0x20000
	s_addc_u32 s23, s23, 0
	s_mov_b32 m0, s31
	v_lshl_add_u64 v[230:231], s[22:23], 0, v[0:1]
	ds_read_b128 v[154:157], v137 offset:32768
	ds_read_b128 v[158:161], v137 offset:33792
	ds_read_b128 v[176:179], v137 offset:34816
	ds_read_b128 v[180:183], v137 offset:35840
	ds_read_b128 v[184:187], v137 offset:36864
	ds_read_b128 v[188:191], v137 offset:37888
	ds_read_b128 v[192:195], v137 offset:38912
	ds_read_b128 v[196:199], v137 offset:39936
	global_load_lds_dwordx4 v[230:231], off
	v_lshl_add_u64 v[230:231], s[22:23], 0, v[130:131]
	s_mov_b32 m0, s34
	s_nop 0
	global_load_lds_dwordx4 v[230:231], off
	s_waitcnt lgkmcnt(8)
	s_barrier
	s_waitcnt lgkmcnt(0)
	s_setprio 1
	s_waitcnt lgkmcnt(0)
	v_mfma_f32_16x16x32_bf16 v[126:129], v[138:141], v[154:157], v[126:129]
	v_mfma_f32_16x16x32_bf16 v[122:125], v[146:149], v[154:157], v[122:125]
	v_mfma_f32_16x16x32_bf16 v[114:117], v[138:141], v[176:179], v[114:117]
	v_mfma_f32_16x16x32_bf16 v[106:109], v[146:149], v[176:179], v[106:109]
	v_mfma_f32_16x16x32_bf16 v[98:101], v[138:141], v[184:187], v[98:101]
	v_mfma_f32_16x16x32_bf16 v[90:93], v[146:149], v[184:187], v[90:93]
	v_mfma_f32_16x16x32_bf16 v[82:85], v[138:141], v[192:195], v[82:85]
	v_mfma_f32_16x16x32_bf16 v[74:77], v[146:149], v[192:195], v[74:77]
	v_mfma_f32_16x16x32_bf16 v[126:129], v[142:145], v[158:161], v[126:129]
	v_mfma_f32_16x16x32_bf16 v[122:125], v[150:153], v[158:161], v[122:125]
	v_mfma_f32_16x16x32_bf16 v[114:117], v[142:145], v[180:183], v[114:117]
	v_mfma_f32_16x16x32_bf16 v[106:109], v[150:153], v[180:183], v[106:109]
	v_mfma_f32_16x16x32_bf16 v[98:101], v[142:145], v[188:191], v[98:101]
	v_mfma_f32_16x16x32_bf16 v[90:93], v[150:153], v[188:191], v[90:93]
	v_mfma_f32_16x16x32_bf16 v[82:85], v[142:145], v[196:199], v[82:85]
	v_mfma_f32_16x16x32_bf16 v[74:77], v[150:153], v[196:199], v[74:77]
	s_setprio 0
	s_barrier
	s_add_i32 s22, 0, 0x1c000
	s_add_i32 s23, s44, s27
	v_add_u32_e32 v169, s22, v136
	v_lshl_add_u64 v[200:201], v[200:201], 0, s[92:93]
	s_mov_b32 m0, s23
	ds_read_b128 v[230:233], v169
	ds_read_b128 v[234:237], v169 offset:1024
	ds_read_b128 v[238:241], v169 offset:2048
	ds_read_b128 v[242:245], v169 offset:3072
	global_load_lds_dwordx4 v[200:201], off
	v_lshl_add_u64 v[200:201], v[246:247], 0, s[92:93]
	s_add_i32 m0, s23, 0x2000
	s_nop 0
	global_load_lds_dwordx4 v[200:201], off
	s_barrier
	s_waitcnt lgkmcnt(0)
	s_setprio 1
	s_waitcnt lgkmcnt(0)
	v_mfma_f32_16x16x32_bf16 v[118:121], v[230:233], v[154:157], v[118:121]
	v_mfma_f32_16x16x32_bf16 v[110:113], v[238:241], v[154:157], v[110:113]
	v_mfma_f32_16x16x32_bf16 v[102:105], v[230:233], v[176:179], v[102:105]
	v_mfma_f32_16x16x32_bf16 v[94:97], v[238:241], v[176:179], v[94:97]
	v_mfma_f32_16x16x32_bf16 v[86:89], v[230:233], v[184:187], v[86:89]
	v_mfma_f32_16x16x32_bf16 v[78:81], v[238:241], v[184:187], v[78:81]
	v_mfma_f32_16x16x32_bf16 v[70:73], v[230:233], v[192:195], v[70:73]
	v_mfma_f32_16x16x32_bf16 v[66:69], v[238:241], v[192:195], v[66:69]
	v_mfma_f32_16x16x32_bf16 v[118:121], v[234:237], v[158:161], v[118:121]
	v_mfma_f32_16x16x32_bf16 v[110:113], v[242:245], v[158:161], v[110:113]
	v_mfma_f32_16x16x32_bf16 v[102:105], v[234:237], v[180:183], v[102:105]
	v_mfma_f32_16x16x32_bf16 v[94:97], v[242:245], v[180:183], v[94:97]
	v_mfma_f32_16x16x32_bf16 v[86:89], v[234:237], v[188:191], v[86:89]
	v_mfma_f32_16x16x32_bf16 v[78:81], v[242:245], v[188:191], v[78:81]
	v_mfma_f32_16x16x32_bf16 v[70:73], v[234:237], v[196:199], v[70:73]
	v_mfma_f32_16x16x32_bf16 v[66:69], v[242:245], v[196:199], v[66:69]
	s_setprio 0
	s_mov_b32 m0, s35
	v_lshl_add_u64 v[200:201], v[248:249], 0, s[92:93]
	s_barrier
	ds_read_b128 v[154:157], v137 offset:49152
	ds_read_b128 v[158:161], v137 offset:50176
	ds_read_b128 v[176:179], v137 offset:51200
	ds_read_b128 v[180:183], v137 offset:52224
	ds_read_b128 v[184:187], v137 offset:53248
	ds_read_b128 v[188:191], v137 offset:54272
	ds_read_b128 v[192:195], v137 offset:55296
	ds_read_b128 v[196:199], v137 offset:56320
	global_load_lds_dwordx4 v[200:201], off
	v_lshl_add_u64 v[200:201], v[250:251], 0, s[92:93]
	s_mov_b32 m0, s36
	s_nop 0
	global_load_lds_dwordx4 v[200:201], off
	s_barrier
	s_waitcnt lgkmcnt(0)
	s_setprio 1
	s_waitcnt lgkmcnt(0)
	v_mfma_f32_16x16x32_bf16 v[62:65], v[138:141], v[154:157], v[62:65]
	v_mfma_f32_16x16x32_bf16 v[58:61], v[146:149], v[154:157], v[58:61]
	v_mfma_f32_16x16x32_bf16 v[50:53], v[138:141], v[176:179], v[50:53]
	v_mfma_f32_16x16x32_bf16 v[42:45], v[146:149], v[176:179], v[42:45]
	v_mfma_f32_16x16x32_bf16 v[34:37], v[138:141], v[184:187], v[34:37]
	v_mfma_f32_16x16x32_bf16 v[26:29], v[146:149], v[184:187], v[26:29]
	v_mfma_f32_16x16x32_bf16 v[18:21], v[138:141], v[192:195], v[18:21]
	v_mfma_f32_16x16x32_bf16 v[10:13], v[146:149], v[192:195], v[10:13]
	v_mfma_f32_16x16x32_bf16 v[62:65], v[142:145], v[158:161], v[62:65]
	v_mfma_f32_16x16x32_bf16 v[58:61], v[150:153], v[158:161], v[58:61]
	v_mfma_f32_16x16x32_bf16 v[50:53], v[142:145], v[180:183], v[50:53]
	v_mfma_f32_16x16x32_bf16 v[42:45], v[150:153], v[180:183], v[42:45]
	v_mfma_f32_16x16x32_bf16 v[34:37], v[142:145], v[188:191], v[34:37]
	v_mfma_f32_16x16x32_bf16 v[26:29], v[150:153], v[188:191], v[26:29]
	v_mfma_f32_16x16x32_bf16 v[18:21], v[142:145], v[196:199], v[18:21]
	v_mfma_f32_16x16x32_bf16 v[10:13], v[150:153], v[196:199], v[10:13]
	s_setprio 0
	s_barrier
	s_add_u32 s20, s20, 0x20080
	s_addc_u32 s21, s21, 0
	s_add_i32 s22, s22, s27
	v_lshl_add_u64 v[138:139], s[20:21], 0, v[0:1]
	s_mov_b32 m0, s22
	s_nop 0
	global_load_lds_dwordx4 v[138:139], off
	v_lshl_add_u64 v[138:139], s[20:21], 0, v[130:131]
	s_add_i32 m0, s22, 0x2000
	s_nop 0
	global_load_lds_dwordx4 v[138:139], off
	s_waitcnt vmcnt(6)
	s_barrier
	s_setprio 1
	v_mfma_f32_16x16x32_bf16 v[54:57], v[230:233], v[154:157], v[54:57]
	v_mfma_f32_16x16x32_bf16 v[46:49], v[238:241], v[154:157], v[46:49]
	v_mfma_f32_16x16x32_bf16 v[38:41], v[230:233], v[176:179], v[38:41]
	v_mfma_f32_16x16x32_bf16 v[30:33], v[238:241], v[176:179], v[30:33]
	v_mfma_f32_16x16x32_bf16 v[22:25], v[230:233], v[184:187], v[22:25]
	v_mfma_f32_16x16x32_bf16 v[14:17], v[238:241], v[184:187], v[14:17]
	v_mfma_f32_16x16x32_bf16 v[6:9], v[230:233], v[192:195], v[6:9]
	v_mfma_f32_16x16x32_bf16 v[2:5], v[238:241], v[192:195], v[2:5]
	v_mfma_f32_16x16x32_bf16 v[54:57], v[234:237], v[158:161], v[54:57]
	v_mfma_f32_16x16x32_bf16 v[46:49], v[242:245], v[158:161], v[46:49]
	v_mfma_f32_16x16x32_bf16 v[38:41], v[234:237], v[180:183], v[38:41]
	v_mfma_f32_16x16x32_bf16 v[30:33], v[242:245], v[180:183], v[30:33]
	v_mfma_f32_16x16x32_bf16 v[22:25], v[234:237], v[188:191], v[22:25]
	v_mfma_f32_16x16x32_bf16 v[14:17], v[242:245], v[188:191], v[14:17]
	v_mfma_f32_16x16x32_bf16 v[6:9], v[234:237], v[196:199], v[6:9]
	v_mfma_f32_16x16x32_bf16 v[2:5], v[242:245], v[196:199], v[2:5]
	s_setprio 0
	s_add_i32 s43, s43, 2
	s_add_u32 s41, s41, 0x100
	s_addc_u32 s42, s42, 0
	s_add_u32 s8, s8, 0x100
	s_addc_u32 s9, s9, 0
	s_cmp_gt_u32 s43, 1
	s_barrier
	s_cbranch_scc0 .LBB0_893
	v_mov_b32_e32 v138, v163
	s_lshl_b32 s7, s7, 8
	v_and_b32_e32 v139, 15, v138
	v_and_b32_e32 v140, 0xc0, v138
	v_ashrrev_i32_e32 v141, 2, v138
	v_lshrrev_b32_e32 v138, 1, v138
	v_and_b32_e32 v138, 24, v138
	v_or3_b32 v138, v140, s7, v138
	s_movk_i32 s7, 0xffc0
	v_and_or_b32 v139, v141, s7, v139
	v_lshl_add_u32 v140, s6, 8, v139
	v_ashrrev_i32_e32 v141, 31, v140
	s_mov_b32 s20, 0x3db504f3
	s_movk_i32 s6, 0x1ff
	v_readlane_b32 s8, v254, 35
	v_lshlrev_b64 v[142:143], 11, v[140:141]
	v_pk_mul_f32 v[144:145], v[128:129], s[20:21] op_sel_hi:[1,0]
	v_pk_mul_f32 v[146:147], v[126:127], s[20:21] op_sel_hi:[1,0]
	v_pk_mul_f32 v[148:149], v[124:125], s[20:21] op_sel_hi:[1,0]
	v_pk_mul_f32 v[150:151], v[122:123], s[20:21] op_sel_hi:[1,0]
	v_cmp_lt_i32_e32 vcc, s6, v138
	v_readlane_b32 s9, v254, 36
	v_ashrrev_i32_e32 v139, 31, v138
	v_cndmask_b32_e32 v141, v129, v145, vcc
	v_cndmask_b32_e32 v144, v128, v144, vcc
	v_cndmask_b32_e32 v127, v127, v147, vcc
	v_cndmask_b32_e32 v126, v126, v146, vcc
	v_cndmask_b32_e32 v145, v125, v149, vcc
	v_cndmask_b32_e32 v146, v124, v148, vcc
	v_cndmask_b32_e32 v147, v123, v151, vcc
	v_cndmask_b32_e32 v148, v122, v150, vcc
	v_lshl_add_u64 v[122:123], s[8:9], 0, v[142:143]
	v_lshlrev_b64 v[128:129], 1, v[138:139]
	v_lshl_add_u64 v[122:123], v[122:123], 0, v[128:129]
	v_cvt_pk_bf16_f32 v124, v126, v127
	v_cvt_pk_bf16_f32 v125, v144, v141
	v_cvt_pk_bf16_f32 v126, v148, v147
	v_cvt_pk_bf16_f32 v127, v146, v145
	v_or_b32_e32 v141, 32, v138
	global_store_dwordx4 v[122:123], v[124:127], off
	v_pk_mul_f32 v[138:139], v[112:113], s[20:21] op_sel_hi:[1,0]
	v_pk_mul_f32 v[142:143], v[110:111], s[20:21] op_sel_hi:[1,0]
	v_pk_mul_f32 v[124:125], v[120:121], s[20:21] op_sel_hi:[1,0]
	v_pk_mul_f32 v[126:127], v[118:119], s[20:21] op_sel_hi:[1,0]
	v_cmp_lt_i32_e64 s[6:7], s6, v141
	s_nop 1
	v_cndmask_b32_e64 v121, v121, v125, s[6:7]
	v_cndmask_b32_e64 v120, v120, v124, s[6:7]
	v_cndmask_b32_e64 v119, v119, v127, s[6:7]
	v_cndmask_b32_e64 v118, v118, v126, s[6:7]
	v_cndmask_b32_e64 v113, v113, v139, s[6:7]
	v_cndmask_b32_e64 v124, v112, v138, s[6:7]
	v_cndmask_b32_e64 v112, v111, v143, s[6:7]
	v_cndmask_b32_e64 v125, v110, v142, s[6:7]
	v_cvt_pk_bf16_f32 v110, v118, v119
	v_cvt_pk_bf16_f32 v111, v120, v121
	v_cvt_pk_bf16_f32 v112, v125, v112
	v_cvt_pk_bf16_f32 v113, v124, v113
	global_store_dwordx4 v[122:123], v[110:113], off offset:64
	v_pk_mul_f32 v[118:119], v[114:115], s[20:21] op_sel_hi:[1,0]
	v_pk_mul_f32 v[120:121], v[108:109], s[20:21] op_sel_hi:[1,0]
	v_or_b32_e32 v110, 16, v140
	v_ashrrev_i32_e32 v111, 31, v110
	v_lshlrev_b64 v[110:111], 11, v[110:111]
	v_pk_mul_f32 v[112:113], v[116:117], s[20:21] op_sel_hi:[1,0]
	v_pk_mul_f32 v[124:125], v[106:107], s[20:21] op_sel_hi:[1,0]
	v_cndmask_b32_e32 v113, v117, v113, vcc
	v_cndmask_b32_e32 v112, v116, v112, vcc
	v_cndmask_b32_e32 v115, v115, v119, vcc
	v_cndmask_b32_e32 v114, v114, v118, vcc
	v_cndmask_b32_e32 v109, v109, v121, vcc
	v_cndmask_b32_e32 v116, v108, v120, vcc
	v_cndmask_b32_e32 v108, v107, v125, vcc
	v_cndmask_b32_e32 v117, v106, v124, vcc
	v_lshl_add_u64 v[106:107], s[8:9], 0, v[110:111]
	v_lshl_add_u64 v[110:111], v[106:107], 0, v[128:129]
	v_cvt_pk_bf16_f32 v106, v114, v115
	v_cvt_pk_bf16_f32 v107, v112, v113
	v_cvt_pk_bf16_f32 v108, v117, v108
	v_cvt_pk_bf16_f32 v109, v116, v109
	global_store_dwordx4 v[110:111], v[106:109], off
	v_pk_mul_f32 v[112:113], v[96:97], s[20:21] op_sel_hi:[1,0]
	v_pk_mul_f32 v[114:115], v[94:95], s[20:21] op_sel_hi:[1,0]
	v_pk_mul_f32 v[106:107], v[104:105], s[20:21] op_sel_hi:[1,0]
	v_pk_mul_f32 v[108:109], v[102:103], s[20:21] op_sel_hi:[1,0]
	v_cndmask_b32_e64 v105, v105, v107, s[6:7]
	v_cndmask_b32_e64 v104, v104, v106, s[6:7]
	v_cndmask_b32_e64 v103, v103, v109, s[6:7]
	v_cndmask_b32_e64 v102, v102, v108, s[6:7]
	v_cndmask_b32_e64 v97, v97, v113, s[6:7]
	v_cndmask_b32_e64 v106, v96, v112, s[6:7]
	v_cndmask_b32_e64 v96, v95, v115, s[6:7]
	v_cndmask_b32_e64 v107, v94, v114, s[6:7]
	v_cvt_pk_bf16_f32 v94, v102, v103
	v_cvt_pk_bf16_f32 v95, v104, v105
	v_cvt_pk_bf16_f32 v96, v107, v96
	v_cvt_pk_bf16_f32 v97, v106, v97
	global_store_dwordx4 v[110:111], v[94:97], off offset:64
	v_pk_mul_f32 v[102:103], v[98:99], s[20:21] op_sel_hi:[1,0]
	v_pk_mul_f32 v[104:105], v[92:93], s[20:21] op_sel_hi:[1,0]
	v_or_b32_e32 v94, 32, v140
	v_ashrrev_i32_e32 v95, 31, v94
	v_lshlrev_b64 v[94:95], 11, v[94:95]
	v_pk_mul_f32 v[96:97], v[100:101], s[20:21] op_sel_hi:[1,0]
	v_pk_mul_f32 v[106:107], v[90:91], s[20:21] op_sel_hi:[1,0]
	v_cndmask_b32_e32 v97, v101, v97, vcc
	v_cndmask_b32_e32 v96, v100, v96, vcc
	v_cndmask_b32_e32 v99, v99, v103, vcc
	v_cndmask_b32_e32 v98, v98, v102, vcc
	v_cndmask_b32_e32 v93, v93, v105, vcc
	v_cndmask_b32_e32 v100, v92, v104, vcc
	v_cndmask_b32_e32 v92, v91, v107, vcc
	v_cndmask_b32_e32 v101, v90, v106, vcc
	v_lshl_add_u64 v[90:91], s[8:9], 0, v[94:95]
	v_lshl_add_u64 v[94:95], v[90:91], 0, v[128:129]
	v_cvt_pk_bf16_f32 v90, v98, v99
	v_cvt_pk_bf16_f32 v91, v96, v97
	v_cvt_pk_bf16_f32 v92, v101, v92
	v_cvt_pk_bf16_f32 v93, v100, v93
	global_store_dwordx4 v[94:95], v[90:93], off
	v_pk_mul_f32 v[96:97], v[80:81], s[20:21] op_sel_hi:[1,0]
	v_pk_mul_f32 v[98:99], v[78:79], s[20:21] op_sel_hi:[1,0]
	v_pk_mul_f32 v[90:91], v[88:89], s[20:21] op_sel_hi:[1,0]
	v_pk_mul_f32 v[92:93], v[86:87], s[20:21] op_sel_hi:[1,0]
	v_cndmask_b32_e64 v89, v89, v91, s[6:7]
	v_cndmask_b32_e64 v88, v88, v90, s[6:7]
	v_cndmask_b32_e64 v87, v87, v93, s[6:7]
	v_cndmask_b32_e64 v86, v86, v92, s[6:7]
	v_cndmask_b32_e64 v81, v81, v97, s[6:7]
	v_cndmask_b32_e64 v90, v80, v96, s[6:7]
	v_cndmask_b32_e64 v80, v79, v99, s[6:7]
	v_cndmask_b32_e64 v91, v78, v98, s[6:7]
	v_cvt_pk_bf16_f32 v78, v86, v87
	v_cvt_pk_bf16_f32 v79, v88, v89
	v_cvt_pk_bf16_f32 v80, v91, v80
	v_cvt_pk_bf16_f32 v81, v90, v81
	global_store_dwordx4 v[94:95], v[78:81], off offset:64
	v_pk_mul_f32 v[86:87], v[82:83], s[20:21] op_sel_hi:[1,0]
	v_pk_mul_f32 v[88:89], v[76:77], s[20:21] op_sel_hi:[1,0]
	v_or_b32_e32 v78, 48, v140
	v_ashrrev_i32_e32 v79, 31, v78
	v_lshlrev_b64 v[78:79], 11, v[78:79]
	v_pk_mul_f32 v[80:81], v[84:85], s[20:21] op_sel_hi:[1,0]
	v_pk_mul_f32 v[90:91], v[74:75], s[20:21] op_sel_hi:[1,0]
	v_cndmask_b32_e32 v81, v85, v81, vcc
	v_cndmask_b32_e32 v80, v84, v80, vcc
	v_cndmask_b32_e32 v83, v83, v87, vcc
	v_cndmask_b32_e32 v82, v82, v86, vcc
	v_cndmask_b32_e32 v77, v77, v89, vcc
	v_cndmask_b32_e32 v84, v76, v88, vcc
	v_cndmask_b32_e32 v76, v75, v91, vcc
	v_cndmask_b32_e32 v85, v74, v90, vcc
	v_lshl_add_u64 v[74:75], s[8:9], 0, v[78:79]
	v_lshl_add_u64 v[78:79], v[74:75], 0, v[128:129]
	v_cvt_pk_bf16_f32 v74, v82, v83
	v_cvt_pk_bf16_f32 v75, v80, v81
	v_cvt_pk_bf16_f32 v76, v85, v76
	v_cvt_pk_bf16_f32 v77, v84, v77
	global_store_dwordx4 v[78:79], v[74:77], off
	v_pk_mul_f32 v[80:81], v[68:69], s[20:21] op_sel_hi:[1,0]
	v_pk_mul_f32 v[82:83], v[66:67], s[20:21] op_sel_hi:[1,0]
	v_pk_mul_f32 v[74:75], v[72:73], s[20:21] op_sel_hi:[1,0]
	v_pk_mul_f32 v[76:77], v[70:71], s[20:21] op_sel_hi:[1,0]
	v_cndmask_b32_e64 v73, v73, v75, s[6:7]
	v_cndmask_b32_e64 v72, v72, v74, s[6:7]
	v_cndmask_b32_e64 v71, v71, v77, s[6:7]
	v_cndmask_b32_e64 v70, v70, v76, s[6:7]
	v_cndmask_b32_e64 v69, v69, v81, s[6:7]
	v_cndmask_b32_e64 v74, v68, v80, s[6:7]
	v_cndmask_b32_e64 v68, v67, v83, s[6:7]
	v_cndmask_b32_e64 v75, v66, v82, s[6:7]
	v_cvt_pk_bf16_f32 v66, v70, v71
	v_cvt_pk_bf16_f32 v67, v72, v73
	v_cvt_pk_bf16_f32 v68, v75, v68
	v_cvt_pk_bf16_f32 v69, v74, v69
	global_store_dwordx4 v[78:79], v[66:69], off offset:64
	s_mov_b64 s[8:9], 0x40000
	v_pk_mul_f32 v[70:71], v[60:61], s[20:21] op_sel_hi:[1,0]
	v_pk_mul_f32 v[66:67], v[64:65], s[20:21] op_sel_hi:[1,0]
	v_pk_mul_f32 v[68:69], v[62:63], s[20:21] op_sel_hi:[1,0]
	v_pk_mul_f32 v[72:73], v[58:59], s[20:21] op_sel_hi:[1,0]
	v_cndmask_b32_e32 v65, v65, v67, vcc
	v_cndmask_b32_e32 v64, v64, v66, vcc
	v_cndmask_b32_e32 v66, v63, v69, vcc
	v_cndmask_b32_e32 v67, v62, v68, vcc
	v_lshl_add_u64 v[62:63], v[122:123], 0, s[8:9]
	s_mov_b32 s8, 0x40000
	v_cndmask_b32_e32 v61, v61, v71, vcc
	v_cndmask_b32_e32 v68, v60, v70, vcc
	v_cndmask_b32_e32 v60, v59, v73, vcc
	v_cndmask_b32_e32 v69, v58, v72, vcc
	v_cvt_pk_bf16_f32 v59, v64, v65
	v_add_co_u32_e64 v64, s[8:9], s8, v122
	v_cvt_pk_bf16_f32 v58, v67, v66
	v_cvt_pk_bf16_f32 v60, v69, v60
	v_cvt_pk_bf16_f32 v61, v68, v61
	v_addc_co_u32_e64 v65, s[8:9], 0, v123, s[8:9]
	global_store_dwordx4 v[64:65], v[58:61], off
	v_pk_mul_f32 v[64:65], v[48:49], s[20:21] op_sel_hi:[1,0]
	v_pk_mul_f32 v[66:67], v[46:47], s[20:21] op_sel_hi:[1,0]
	v_pk_mul_f32 v[58:59], v[56:57], s[20:21] op_sel_hi:[1,0]
	v_pk_mul_f32 v[60:61], v[54:55], s[20:21] op_sel_hi:[1,0]
	v_cndmask_b32_e64 v57, v57, v59, s[6:7]
	v_cndmask_b32_e64 v56, v56, v58, s[6:7]
	v_cndmask_b32_e64 v55, v55, v61, s[6:7]
	v_cndmask_b32_e64 v54, v54, v60, s[6:7]
	v_cndmask_b32_e64 v49, v49, v65, s[6:7]
	v_cndmask_b32_e64 v58, v48, v64, s[6:7]
	v_cndmask_b32_e64 v48, v47, v67, s[6:7]
	v_cndmask_b32_e64 v59, v46, v66, s[6:7]
	v_cvt_pk_bf16_f32 v46, v54, v55
	v_cvt_pk_bf16_f32 v47, v56, v57
	v_cvt_pk_bf16_f32 v48, v59, v48
	v_cvt_pk_bf16_f32 v49, v58, v49
	global_store_dwordx4 v[62:63], v[46:49], off offset:64
	v_pk_mul_f32 v[54:55], v[44:45], s[20:21] op_sel_hi:[1,0]
	v_pk_mul_f32 v[56:57], v[42:43], s[20:21] op_sel_hi:[1,0]
	v_pk_mul_f32 v[48:49], v[50:51], s[20:21] op_sel_hi:[1,0]
	v_pk_mul_f32 v[46:47], v[52:53], s[20:21] op_sel_hi:[1,0]
	v_cndmask_b32_e32 v49, v51, v49, vcc
	v_cndmask_b32_e32 v48, v50, v48, vcc
	s_mov_b64 s[8:9], 0x48000
	v_cndmask_b32_e32 v53, v53, v47, vcc
	v_cndmask_b32_e32 v52, v52, v46, vcc
	v_cndmask_b32_e32 v45, v45, v55, vcc
	v_cndmask_b32_e32 v50, v44, v54, vcc
	v_cndmask_b32_e32 v44, v43, v57, vcc
	v_cndmask_b32_e32 v51, v42, v56, vcc
	v_lshl_add_u64 v[46:47], v[122:123], 0, s[8:9]
	v_cvt_pk_bf16_f32 v42, v48, v49
	v_add_co_u32_e64 v48, s[8:9], s95, v122
	v_cvt_pk_bf16_f32 v43, v52, v53
	v_cvt_pk_bf16_f32 v44, v51, v44
	v_cvt_pk_bf16_f32 v45, v50, v45
	v_addc_co_u32_e64 v49, s[8:9], 0, v123, s[8:9]
	global_store_dwordx4 v[48:49], v[42:45], off
	v_pk_mul_f32 v[48:49], v[32:33], s[20:21] op_sel_hi:[1,0]
	v_pk_mul_f32 v[50:51], v[30:31], s[20:21] op_sel_hi:[1,0]
	v_pk_mul_f32 v[42:43], v[40:41], s[20:21] op_sel_hi:[1,0]
	v_pk_mul_f32 v[44:45], v[38:39], s[20:21] op_sel_hi:[1,0]
	v_cndmask_b32_e64 v41, v41, v43, s[6:7]
	v_cndmask_b32_e64 v40, v40, v42, s[6:7]
	v_cndmask_b32_e64 v39, v39, v45, s[6:7]
	v_cndmask_b32_e64 v38, v38, v44, s[6:7]
	v_cndmask_b32_e64 v33, v33, v49, s[6:7]
	v_cndmask_b32_e64 v42, v32, v48, s[6:7]
	v_cndmask_b32_e64 v32, v31, v51, s[6:7]
	v_cndmask_b32_e64 v43, v30, v50, s[6:7]
	v_cvt_pk_bf16_f32 v30, v38, v39
	v_cvt_pk_bf16_f32 v31, v40, v41
	v_cvt_pk_bf16_f32 v32, v43, v32
	v_cvt_pk_bf16_f32 v33, v42, v33
	global_store_dwordx4 v[46:47], v[30:33], off offset:64
	s_mov_b64 s[8:9], 0x50000
	v_pk_mul_f32 v[38:39], v[28:29], s[20:21] op_sel_hi:[1,0]
	v_pk_mul_f32 v[30:31], v[36:37], s[20:21] op_sel_hi:[1,0]
	v_pk_mul_f32 v[32:33], v[34:35], s[20:21] op_sel_hi:[1,0]
	v_pk_mul_f32 v[40:41], v[26:27], s[20:21] op_sel_hi:[1,0]
	v_cndmask_b32_e32 v37, v37, v31, vcc
	v_cndmask_b32_e32 v36, v36, v30, vcc
	v_cndmask_b32_e32 v33, v35, v33, vcc
	v_cndmask_b32_e32 v32, v34, v32, vcc
	v_lshl_add_u64 v[30:31], v[122:123], 0, s[8:9]
	s_mov_b32 s8, 0x50000
	v_cndmask_b32_e32 v29, v29, v39, vcc
	v_cndmask_b32_e32 v34, v28, v38, vcc
	v_cndmask_b32_e32 v28, v27, v41, vcc
	v_cndmask_b32_e32 v35, v26, v40, vcc
	v_cvt_pk_bf16_f32 v26, v32, v33
	v_add_co_u32_e64 v32, s[8:9], s8, v122
	v_cvt_pk_bf16_f32 v27, v36, v37
	v_cvt_pk_bf16_f32 v28, v35, v28
	v_cvt_pk_bf16_f32 v29, v34, v29
	v_addc_co_u32_e64 v33, s[8:9], 0, v123, s[8:9]
	global_store_dwordx4 v[32:33], v[26:29], off
	v_pk_mul_f32 v[32:33], v[16:17], s[20:21] op_sel_hi:[1,0]
	v_pk_mul_f32 v[34:35], v[14:15], s[20:21] op_sel_hi:[1,0]
	v_pk_mul_f32 v[26:27], v[24:25], s[20:21] op_sel_hi:[1,0]
	v_pk_mul_f32 v[28:29], v[22:23], s[20:21] op_sel_hi:[1,0]
	v_cndmask_b32_e64 v25, v25, v27, s[6:7]
	v_cndmask_b32_e64 v24, v24, v26, s[6:7]
	v_cndmask_b32_e64 v23, v23, v29, s[6:7]
	v_cndmask_b32_e64 v22, v22, v28, s[6:7]
	v_cndmask_b32_e64 v17, v17, v33, s[6:7]
	v_cndmask_b32_e64 v26, v16, v32, s[6:7]
	v_cndmask_b32_e64 v16, v15, v35, s[6:7]
	v_cndmask_b32_e64 v27, v14, v34, s[6:7]
	v_cvt_pk_bf16_f32 v14, v22, v23
	v_cvt_pk_bf16_f32 v15, v24, v25
	v_cvt_pk_bf16_f32 v16, v27, v16
	v_cvt_pk_bf16_f32 v17, v26, v17
	global_store_dwordx4 v[30:31], v[14:17], off offset:64
	s_mov_b64 s[8:9], 0x58000
	v_pk_mul_f32 v[22:23], v[12:13], s[20:21] op_sel_hi:[1,0]
	v_pk_mul_f32 v[14:15], v[20:21], s[20:21] op_sel_hi:[1,0]
	v_pk_mul_f32 v[16:17], v[18:19], s[20:21] op_sel_hi:[1,0]
	v_pk_mul_f32 v[24:25], v[10:11], s[20:21] op_sel_hi:[1,0]
	v_cndmask_b32_e32 v21, v21, v15, vcc
	v_cndmask_b32_e32 v20, v20, v14, vcc
	v_cndmask_b32_e32 v17, v19, v17, vcc
	v_cndmask_b32_e32 v16, v18, v16, vcc
	v_lshl_add_u64 v[14:15], v[122:123], 0, s[8:9]
	s_mov_b32 s8, 0x58000
	v_cndmask_b32_e32 v13, v13, v23, vcc
	v_cndmask_b32_e32 v18, v12, v22, vcc
	v_cndmask_b32_e32 v12, v11, v25, vcc
	v_cndmask_b32_e32 v19, v10, v24, vcc
	v_cvt_pk_bf16_f32 v10, v16, v17
	v_add_co_u32_e32 v16, vcc, s8, v122
	v_cvt_pk_bf16_f32 v11, v20, v21
	v_cvt_pk_bf16_f32 v12, v19, v12
	v_cvt_pk_bf16_f32 v13, v18, v13
	v_addc_co_u32_e32 v17, vcc, 0, v123, vcc
	global_store_dwordx4 v[16:17], v[10:13], off
	v_pk_mul_f32 v[16:17], v[4:5], s[20:21] op_sel_hi:[1,0]
	v_pk_mul_f32 v[18:19], v[2:3], s[20:21] op_sel_hi:[1,0]
	v_pk_mul_f32 v[10:11], v[8:9], s[20:21] op_sel_hi:[1,0]
	v_pk_mul_f32 v[12:13], v[6:7], s[20:21] op_sel_hi:[1,0]
	v_cndmask_b32_e64 v9, v9, v11, s[6:7]
	v_cndmask_b32_e64 v8, v8, v10, s[6:7]
	v_cndmask_b32_e64 v7, v7, v13, s[6:7]
	v_cndmask_b32_e64 v6, v6, v12, s[6:7]
	v_cndmask_b32_e64 v5, v5, v17, s[6:7]
	v_cndmask_b32_e64 v10, v4, v16, s[6:7]
	v_cndmask_b32_e64 v4, v3, v19, s[6:7]
	v_cndmask_b32_e64 v11, v2, v18, s[6:7]
	v_cvt_pk_bf16_f32 v2, v6, v7
	v_cvt_pk_bf16_f32 v3, v8, v9
	v_cvt_pk_bf16_f32 v4, v11, v4
	v_cvt_pk_bf16_f32 v5, v10, v5
	s_and_b64 vcc, exec, s[4:5]
	s_mov_b32 s7, s10
	s_mov_b32 s6, s12
	s_mov_b64 s[8:9], s[18:19]
	s_mov_b64 s[20:21], s[16:17]
	global_store_dwordx4 v[14:15], v[2:5], off offset:64
	s_cbranch_vccz .LBB0_890
	s_waitcnt vmcnt(0)
	s_cmpk_gt_u32 s2, 0xff
	s_cbranch_scc1 .LBB0_897
	s_barrier
